# SwiGLU epilogue: exponent-argument multiply and V*(1+e) fma as packed f32 ops (8 fewer VALU instructions per 8 outputs)
# speedup vs baseline: 1.0486x; 1.0006x over previous
; __device__ __forceinline__ float rs_from(const float* p, int n4, float inv_n) {
;     float s = 0.f;
;     for (int i = 0; i < n4; ++i) { const f32x4 v = *(const f32x4*)(p + 4 * i); s += (v[0] + v[1]) + (v[2] + v[3]); }
;     return rsqrtf(s * inv_n + EPS);
; }
;     __device__ __forceinline__ void operator()(AccRef acc, const pg8::Unit& u, int wr, int wc, int fr, int fq) const {
;         const int row0 = u.pm * 256 + wr * 64 + fr, col0 = u.pn * 128 + wc * 32 + 8 * fq;
; #pragma unroll
;         for (int ai = 0; ai < 2; ++ai)
; #pragma unroll
;             for (int m = 0; m < 4; ++m) {
;                 const int row = row0 + ai * 128 + m * 16;
;                 const float rs = rs_from(ssp + (size_t)row * 16, 4, 1.0f / 1024.0f);
;                 f32x4 o[2];
; #pragma unroll
;                 for (int n = 0; n < 2; ++n)
; #pragma unroll
;                     for (int j = 0; j < 4; ++j) {
;                         const float g = acc[ai][0][m][n][j] * rs, up = acc[ai][1][m][n][j] * rs;
;                         o[n][j] = g * __builtin_amdgcn_rcpf(1.0f + __expf(-g)) * up;
;                     }
;                 *(u32x4*)(act + (size_t)row * FF + col0) = pack8(o[0], o[1]);
.LBB0_376:
.Lswi_beg0:
	v_add_u32_e32 v249, 0x2000, v247
	global_load_dwordx4 v[154:157], v249, s[46:47]
	global_load_dwordx4 v[158:161], v249, s[46:47] offset:1024
	global_load_dwordx4 v[162:165], v249, s[46:47] offset:2048
	global_load_dwordx4 v[166:169], v249, s[46:47] offset:3072
	v_mbcnt_lo_u32_b32 v170, -1, 0
	v_mbcnt_hi_u32_b32 v170, -1, v170
	v_xor_b32_e32 v171, 16, v170
	v_xor_b32_e32 v172, 32, v170
	v_lshlrev_b32_e32 v171, 2, v171
	v_lshlrev_b32_e32 v172, 2, v172
	v_lshl_or_b32 v173, s61, 7, v148
	v_lshlrev_b32_e32 v173, 1, v173
	v_mad_u32_u24 v248, v246, s51, v173
	s_waitcnt vmcnt(12)
	v_add_f32_e32 v230, v230, v231
	v_add_f32_e32 v232, v232, v233
	v_add_f32_e32 v234, v234, v235
	v_add_f32_e32 v236, v236, v237
	v_add_f32_e32 v238, v238, v239
	v_add_f32_e32 v240, v240, v241
	v_add_f32_e32 v242, v242, v243
	v_add_f32_e32 v244, v244, v245
	v_add_f32_e32 v230, v230, v232
	v_add_f32_e32 v234, v234, v236
	v_add_f32_e32 v238, v238, v240
	v_add_f32_e32 v242, v242, v244
	ds_bpermute_b32 v231, v171, v230
	ds_bpermute_b32 v235, v171, v234
	ds_bpermute_b32 v239, v171, v238
	ds_bpermute_b32 v243, v171, v242
	s_waitcnt lgkmcnt(0)
	v_add_f32_e32 v230, v230, v231
	v_add_f32_e32 v234, v234, v235
	v_add_f32_e32 v238, v238, v239
	v_add_f32_e32 v242, v242, v243
	ds_bpermute_b32 v231, v172, v230
	ds_bpermute_b32 v235, v172, v234
	ds_bpermute_b32 v239, v172, v238
	ds_bpermute_b32 v243, v172, v242
	s_waitcnt lgkmcnt(0)
	v_add_f32_e32 v230, v230, v231
	v_add_f32_e32 v234, v234, v235
	v_add_f32_e32 v238, v238, v239
	v_add_f32_e32 v242, v242, v243
	v_fmamk_f32 v232, v230, 0x3a800000, v152
	v_fmamk_f32 v236, v234, 0x3a800000, v152
	v_fmamk_f32 v240, v238, 0x3a800000, v152
	v_fmamk_f32 v244, v242, 0x3a800000, v152
	v_rsq_f32_e32 v230, v232
	v_rsq_f32_e32 v234, v236
	v_rsq_f32_e32 v238, v240
	v_rsq_f32_e32 v242, v244
	s_nop 0
	v_mul_f32_e32 v230, 0xbfb8aa3b, v230
	v_mul_f32_e32 v234, 0xbfb8aa3b, v234
	v_mul_f32_e32 v238, 0xbfb8aa3b, v238
	v_mul_f32_e32 v242, 0xbfb8aa3b, v242
	v_pk_mul_f32 v[176:177], v[116:117], v[230:231] op_sel_hi:[1,0]
	v_pk_mul_f32 v[178:179], v[118:119], v[230:231] op_sel_hi:[1,0]
	v_pk_mul_f32 v[180:181], v[112:113], v[230:231] op_sel_hi:[1,0]
	v_pk_mul_f32 v[182:183], v[114:115], v[230:231] op_sel_hi:[1,0]
	v_exp_f32_e32 v176, v176
	v_exp_f32_e32 v177, v177
	v_exp_f32_e32 v178, v178
	v_exp_f32_e32 v179, v179
	v_exp_f32_e32 v180, v180
	v_exp_f32_e32 v181, v181
	v_exp_f32_e32 v182, v182
	v_exp_f32_e32 v183, v183
	v_pk_fma_f32 v[176:177], v[176:177], v[232:233], v[232:233] op_sel_hi:[1,0,0]
	v_pk_fma_f32 v[178:179], v[178:179], v[232:233], v[232:233] op_sel_hi:[1,0,0]
	v_pk_fma_f32 v[180:181], v[180:181], v[232:233], v[232:233] op_sel_hi:[1,0,0]
	v_pk_fma_f32 v[182:183], v[182:183], v[232:233], v[232:233] op_sel_hi:[1,0,0]
	v_rcp_f32_e32 v176, v176
	v_rcp_f32_e32 v177, v177
	v_rcp_f32_e32 v178, v178
	v_rcp_f32_e32 v179, v179
	v_rcp_f32_e32 v180, v180
	v_rcp_f32_e32 v181, v181
	v_rcp_f32_e32 v182, v182
	v_rcp_f32_e32 v183, v183
	v_pk_mul_f32 v[116:117], v[116:117], v[124:125]
	v_pk_mul_f32 v[118:119], v[118:119], v[126:127]
	v_pk_mul_f32 v[112:113], v[112:113], v[120:121]
	v_pk_mul_f32 v[114:115], v[114:115], v[122:123]
	v_pk_mul_f32 v[176:177], v[116:117], v[176:177]
	v_pk_mul_f32 v[178:179], v[118:119], v[178:179]
	v_pk_mul_f32 v[180:181], v[112:113], v[180:181]
	v_pk_mul_f32 v[182:183], v[114:115], v[182:183]
	v_cvt_pk_bf16_f32 v192, v176, v177
	v_cvt_pk_bf16_f32 v193, v178, v179
	v_cvt_pk_bf16_f32 v194, v180, v181
	v_cvt_pk_bf16_f32 v195, v182, v183
	v_mov_b32_e32 v200, v248
	global_store_dwordx4 v200, v[192:195], s[48:49] sc0 sc1
	v_pk_mul_f32 v[184:185], v[100:101], v[234:235] op_sel_hi:[1,0]
	v_pk_mul_f32 v[186:187], v[102:103], v[234:235] op_sel_hi:[1,0]
	v_pk_mul_f32 v[188:189], v[96:97], v[234:235] op_sel_hi:[1,0]
	v_pk_mul_f32 v[190:191], v[98:99], v[234:235] op_sel_hi:[1,0]
	v_exp_f32_e32 v184, v184
	v_exp_f32_e32 v185, v185
	v_exp_f32_e32 v186, v186
	v_exp_f32_e32 v187, v187
	v_exp_f32_e32 v188, v188
	v_exp_f32_e32 v189, v189
	v_exp_f32_e32 v190, v190
	v_exp_f32_e32 v191, v191
	v_pk_fma_f32 v[184:185], v[184:185], v[236:237], v[236:237] op_sel_hi:[1,0,0]
	v_pk_fma_f32 v[186:187], v[186:187], v[236:237], v[236:237] op_sel_hi:[1,0,0]
	v_pk_fma_f32 v[188:189], v[188:189], v[236:237], v[236:237] op_sel_hi:[1,0,0]
	v_pk_fma_f32 v[190:191], v[190:191], v[236:237], v[236:237] op_sel_hi:[1,0,0]
	v_rcp_f32_e32 v184, v184
	v_rcp_f32_e32 v185, v185
	v_rcp_f32_e32 v186, v186
	v_rcp_f32_e32 v187, v187
	v_rcp_f32_e32 v188, v188
	v_rcp_f32_e32 v189, v189
	v_rcp_f32_e32 v190, v190
	v_rcp_f32_e32 v191, v191
	v_pk_mul_f32 v[100:101], v[100:101], v[108:109]
	v_pk_mul_f32 v[102:103], v[102:103], v[110:111]
	v_pk_mul_f32 v[96:97], v[96:97], v[104:105]
	v_pk_mul_f32 v[98:99], v[98:99], v[106:107]
	v_pk_mul_f32 v[184:185], v[100:101], v[184:185]
	v_pk_mul_f32 v[186:187], v[102:103], v[186:187]
	v_pk_mul_f32 v[188:189], v[96:97], v[188:189]
	v_pk_mul_f32 v[190:191], v[98:99], v[190:191]
	v_cvt_pk_bf16_f32 v196, v184, v185
	v_cvt_pk_bf16_f32 v197, v186, v187
	v_cvt_pk_bf16_f32 v198, v188, v189
	v_cvt_pk_bf16_f32 v199, v190, v191
	v_add_u32_e32 v201, 0x16000, v248
	global_store_dwordx4 v201, v[196:199], s[48:49] sc0 sc1
	v_pk_mul_f32 v[176:177], v[84:85], v[238:239] op_sel_hi:[1,0]
	v_pk_mul_f32 v[178:179], v[86:87], v[238:239] op_sel_hi:[1,0]
	v_pk_mul_f32 v[180:181], v[80:81], v[238:239] op_sel_hi:[1,0]
	v_pk_mul_f32 v[182:183], v[82:83], v[238:239] op_sel_hi:[1,0]
	v_exp_f32_e32 v176, v176
	v_exp_f32_e32 v177, v177
	v_exp_f32_e32 v178, v178
	v_exp_f32_e32 v179, v179
	v_exp_f32_e32 v180, v180
	v_exp_f32_e32 v181, v181
	v_exp_f32_e32 v182, v182
;     __device__ __forceinline__ void operator()(AccRef acc, const pg8::Unit& u, int wr, int wc, int fr, int fq) const {
;         const int row0 = u.pm * 256 + wr * 64 + fr, col0 = u.pn * 128 + wc * 32 + 8 * fq;
; #pragma unroll
;         for (int ai = 0; ai < 2; ++ai)
; #pragma unroll
;             for (int m = 0; m < 4; ++m) {
;                 const int row = row0 + ai * 128 + m * 16;
;                 const float rs = rs_from(ssp + (size_t)row * 16, 4, 1.0f / 1024.0f);
;                 f32x4 o[2];
; #pragma unroll
;                 for (int n = 0; n < 2; ++n)
; #pragma unroll
;                     for (int j = 0; j < 4; ++j) {
;                         const float g = acc[ai][0][m][n][j] * rs, up = acc[ai][1][m][n][j] * rs;
;                         o[n][j] = g * __builtin_amdgcn_rcpf(1.0f + __expf(-g)) * up;
;                     }
;                 *(u32x4*)(act + (size_t)row * FF + col0) = pack8(o[0], o[1]);
	v_exp_f32_e32 v183, v183
	v_pk_fma_f32 v[176:177], v[176:177], v[240:241], v[240:241] op_sel_hi:[1,0,0]
	v_pk_fma_f32 v[178:179], v[178:179], v[240:241], v[240:241] op_sel_hi:[1,0,0]
	v_pk_fma_f32 v[180:181], v[180:181], v[240:241], v[240:241] op_sel_hi:[1,0,0]
	v_pk_fma_f32 v[182:183], v[182:183], v[240:241], v[240:241] op_sel_hi:[1,0,0]
	v_rcp_f32_e32 v176, v176
	v_rcp_f32_e32 v177, v177
	v_rcp_f32_e32 v178, v178
	v_rcp_f32_e32 v179, v179
	v_rcp_f32_e32 v180, v180
	v_rcp_f32_e32 v181, v181
	v_rcp_f32_e32 v182, v182
	v_rcp_f32_e32 v183, v183
	v_pk_mul_f32 v[84:85], v[84:85], v[92:93]
	v_pk_mul_f32 v[86:87], v[86:87], v[94:95]
	v_pk_mul_f32 v[80:81], v[80:81], v[88:89]
	v_pk_mul_f32 v[82:83], v[82:83], v[90:91]
	v_pk_mul_f32 v[176:177], v[84:85], v[176:177]
	v_pk_mul_f32 v[178:179], v[86:87], v[178:179]
	v_pk_mul_f32 v[180:181], v[80:81], v[180:181]
	v_pk_mul_f32 v[182:183], v[82:83], v[182:183]
	v_cvt_pk_bf16_f32 v192, v176, v177
	v_cvt_pk_bf16_f32 v193, v178, v179
	v_cvt_pk_bf16_f32 v194, v180, v181
	v_cvt_pk_bf16_f32 v195, v182, v183
	v_add_u32_e32 v200, 0x2c000, v248
	global_store_dwordx4 v200, v[192:195], s[48:49] sc0 sc1
	v_pk_mul_f32 v[184:185], v[68:69], v[242:243] op_sel_hi:[1,0]
	v_pk_mul_f32 v[186:187], v[70:71], v[242:243] op_sel_hi:[1,0]
	v_pk_mul_f32 v[188:189], v[64:65], v[242:243] op_sel_hi:[1,0]
	v_pk_mul_f32 v[190:191], v[66:67], v[242:243] op_sel_hi:[1,0]
	v_exp_f32_e32 v184, v184
	v_exp_f32_e32 v185, v185
	v_exp_f32_e32 v186, v186
	v_exp_f32_e32 v187, v187
	v_exp_f32_e32 v188, v188
	v_exp_f32_e32 v189, v189
	v_exp_f32_e32 v190, v190
	v_exp_f32_e32 v191, v191
	v_pk_fma_f32 v[184:185], v[184:185], v[244:245], v[244:245] op_sel_hi:[1,0,0]
	v_pk_fma_f32 v[186:187], v[186:187], v[244:245], v[244:245] op_sel_hi:[1,0,0]
	v_pk_fma_f32 v[188:189], v[188:189], v[244:245], v[244:245] op_sel_hi:[1,0,0]
	v_pk_fma_f32 v[190:191], v[190:191], v[244:245], v[244:245] op_sel_hi:[1,0,0]
	v_rcp_f32_e32 v184, v184
	v_rcp_f32_e32 v185, v185
	v_rcp_f32_e32 v186, v186
	v_rcp_f32_e32 v187, v187
	v_rcp_f32_e32 v188, v188
	v_rcp_f32_e32 v189, v189
	v_rcp_f32_e32 v190, v190
	v_rcp_f32_e32 v191, v191
	v_pk_mul_f32 v[68:69], v[68:69], v[76:77]
	v_pk_mul_f32 v[70:71], v[70:71], v[78:79]
	v_pk_mul_f32 v[64:65], v[64:65], v[72:73]
	v_pk_mul_f32 v[66:67], v[66:67], v[74:75]
	v_pk_mul_f32 v[184:185], v[68:69], v[184:185]
	v_pk_mul_f32 v[186:187], v[70:71], v[186:187]
	v_pk_mul_f32 v[188:189], v[64:65], v[188:189]
	v_pk_mul_f32 v[190:191], v[66:67], v[190:191]
	v_cvt_pk_bf16_f32 v196, v184, v185
	v_cvt_pk_bf16_f32 v197, v186, v187
	v_cvt_pk_bf16_f32 v198, v188, v189
	v_cvt_pk_bf16_f32 v199, v190, v191
	v_add_u32_e32 v201, 0x42000, v248
	global_store_dwordx4 v201, v[196:199], s[48:49] sc0 sc1
	s_waitcnt vmcnt(4)
	v_add_f32_e32 v154, v154, v155
	v_add_f32_e32 v156, v156, v157
	v_add_f32_e32 v158, v158, v159
	v_add_f32_e32 v160, v160, v161
	v_add_f32_e32 v162, v162, v163
	v_add_f32_e32 v164, v164, v165
	v_add_f32_e32 v166, v166, v167
	v_add_f32_e32 v168, v168, v169
	v_add_f32_e32 v154, v154, v156
	v_add_f32_e32 v158, v158, v160
	v_add_f32_e32 v162, v162, v164
	v_add_f32_e32 v166, v166, v168
	ds_bpermute_b32 v155, v171, v154
	ds_bpermute_b32 v159, v171, v158
	ds_bpermute_b32 v163, v171, v162
	ds_bpermute_b32 v167, v171, v166
	s_waitcnt lgkmcnt(0)
	v_add_f32_e32 v154, v154, v155
	v_add_f32_e32 v158, v158, v159
	v_add_f32_e32 v162, v162, v163
	v_add_f32_e32 v166, v166, v167
	ds_bpermute_b32 v155, v172, v154
	ds_bpermute_b32 v159, v172, v158
	ds_bpermute_b32 v163, v172, v162
	ds_bpermute_b32 v167, v172, v166
	s_waitcnt lgkmcnt(0)
; __device__ __forceinline__ float rs_from(const float* p, int n4, float inv_n) {
;     float s = 0.f;
;     for (int i = 0; i < n4; ++i) { const f32x4 v = *(const f32x4*)(p + 4 * i); s += (v[0] + v[1]) + (v[2] + v[3]); }
;     return rsqrtf(s * inv_n + EPS);
; }
;     __device__ __forceinline__ void operator()(AccRef acc, const pg8::Unit& u, int wr, int wc, int fr, int fq) const {
;         const int row0 = u.pm * 256 + wr * 64 + fr, col0 = u.pn * 128 + wc * 32 + 8 * fq;
; #pragma unroll
;         for (int ai = 0; ai < 2; ++ai)
; #pragma unroll
;             for (int m = 0; m < 4; ++m) {
;                 const int row = row0 + ai * 128 + m * 16;
;                 const float rs = rs_from(ssp + (size_t)row * 16, 4, 1.0f / 1024.0f);
;                 f32x4 o[2];
; #pragma unroll
;                 for (int n = 0; n < 2; ++n)
; #pragma unroll
;                     for (int j = 0; j < 4; ++j) {
;                         const float g = acc[ai][0][m][n][j] * rs, up = acc[ai][1][m][n][j] * rs;
;                         o[n][j] = g * __builtin_amdgcn_rcpf(1.0f + __expf(-g)) * up;
;                     }
;                 *(u32x4*)(act + (size_t)row * FF + col0) = pack8(o[0], o[1]);
	v_add_f32_e32 v154, v154, v155
	v_add_f32_e32 v158, v158, v159
	v_add_f32_e32 v162, v162, v163
	v_add_f32_e32 v166, v166, v167
	v_fmamk_f32 v156, v154, 0x3a800000, v152
	v_fmamk_f32 v160, v158, 0x3a800000, v152
	v_fmamk_f32 v164, v162, 0x3a800000, v152
	v_fmamk_f32 v168, v166, 0x3a800000, v152
	v_rsq_f32_e32 v154, v156
	v_rsq_f32_e32 v158, v160
	v_rsq_f32_e32 v162, v164
	v_rsq_f32_e32 v166, v168
	s_nop 0
	v_mul_f32_e32 v154, 0xbfb8aa3b, v154
	v_mul_f32_e32 v158, 0xbfb8aa3b, v158
	v_mul_f32_e32 v162, 0xbfb8aa3b, v162
	v_mul_f32_e32 v166, 0xbfb8aa3b, v166
	v_pk_mul_f32 v[176:177], v[52:53], v[154:155] op_sel_hi:[1,0]
	v_pk_mul_f32 v[178:179], v[54:55], v[154:155] op_sel_hi:[1,0]
	v_pk_mul_f32 v[180:181], v[48:49], v[154:155] op_sel_hi:[1,0]
	v_pk_mul_f32 v[182:183], v[50:51], v[154:155] op_sel_hi:[1,0]
	v_exp_f32_e32 v176, v176
	v_exp_f32_e32 v177, v177
	v_exp_f32_e32 v178, v178
	v_exp_f32_e32 v179, v179
	v_exp_f32_e32 v180, v180
	v_exp_f32_e32 v181, v181
	v_exp_f32_e32 v182, v182
	v_exp_f32_e32 v183, v183
	v_pk_fma_f32 v[176:177], v[176:177], v[156:157], v[156:157] op_sel_hi:[1,0,0]
	v_pk_fma_f32 v[178:179], v[178:179], v[156:157], v[156:157] op_sel_hi:[1,0,0]
	v_pk_fma_f32 v[180:181], v[180:181], v[156:157], v[156:157] op_sel_hi:[1,0,0]
	v_pk_fma_f32 v[182:183], v[182:183], v[156:157], v[156:157] op_sel_hi:[1,0,0]
	v_rcp_f32_e32 v176, v176
	v_rcp_f32_e32 v177, v177
	v_rcp_f32_e32 v178, v178
	v_rcp_f32_e32 v179, v179
	v_rcp_f32_e32 v180, v180
	v_rcp_f32_e32 v181, v181
	v_rcp_f32_e32 v182, v182
	v_rcp_f32_e32 v183, v183
	v_pk_mul_f32 v[52:53], v[52:53], v[60:61]
	v_pk_mul_f32 v[54:55], v[54:55], v[62:63]
	v_pk_mul_f32 v[48:49], v[48:49], v[56:57]
	v_pk_mul_f32 v[50:51], v[50:51], v[58:59]
	v_pk_mul_f32 v[176:177], v[52:53], v[176:177]
	v_pk_mul_f32 v[178:179], v[54:55], v[178:179]
	v_pk_mul_f32 v[180:181], v[48:49], v[180:181]
	v_pk_mul_f32 v[182:183], v[50:51], v[182:183]
	v_cvt_pk_bf16_f32 v192, v176, v177
	v_cvt_pk_bf16_f32 v193, v178, v179
	v_cvt_pk_bf16_f32 v194, v180, v181
	v_cvt_pk_bf16_f32 v195, v182, v183
	v_add_u32_e32 v200, 0xb0000, v248
	global_store_dwordx4 v200, v[192:195], s[48:49] sc0 sc1
	v_pk_mul_f32 v[184:185], v[36:37], v[158:159] op_sel_hi:[1,0]
	v_pk_mul_f32 v[186:187], v[38:39], v[158:159] op_sel_hi:[1,0]
	v_pk_mul_f32 v[188:189], v[32:33], v[158:159] op_sel_hi:[1,0]
	v_pk_mul_f32 v[190:191], v[34:35], v[158:159] op_sel_hi:[1,0]
	v_exp_f32_e32 v184, v184
	v_exp_f32_e32 v185, v185
	v_exp_f32_e32 v186, v186
	v_exp_f32_e32 v187, v187
	v_exp_f32_e32 v188, v188
	v_exp_f32_e32 v189, v189
	v_exp_f32_e32 v190, v190
	v_exp_f32_e32 v191, v191
	v_pk_fma_f32 v[184:185], v[184:185], v[160:161], v[160:161] op_sel_hi:[1,0,0]
	v_pk_fma_f32 v[186:187], v[186:187], v[160:161], v[160:161] op_sel_hi:[1,0,0]
	v_pk_fma_f32 v[188:189], v[188:189], v[160:161], v[160:161] op_sel_hi:[1,0,0]
	v_pk_fma_f32 v[190:191], v[190:191], v[160:161], v[160:161] op_sel_hi:[1,0,0]
	v_rcp_f32_e32 v184, v184
	v_rcp_f32_e32 v185, v185
	v_rcp_f32_e32 v186, v186
	v_rcp_f32_e32 v187, v187
	v_rcp_f32_e32 v188, v188
	v_rcp_f32_e32 v189, v189
	v_rcp_f32_e32 v190, v190
	v_rcp_f32_e32 v191, v191
	v_pk_mul_f32 v[36:37], v[36:37], v[44:45]
	v_pk_mul_f32 v[38:39], v[38:39], v[46:47]
	v_pk_mul_f32 v[32:33], v[32:33], v[40:41]
	v_pk_mul_f32 v[34:35], v[34:35], v[42:43]
	v_pk_mul_f32 v[184:185], v[36:37], v[184:185]
	v_pk_mul_f32 v[186:187], v[38:39], v[186:187]
	v_pk_mul_f32 v[188:189], v[32:33], v[188:189]
	v_pk_mul_f32 v[190:191], v[34:35], v[190:191]
	v_cvt_pk_bf16_f32 v196, v184, v185
	v_cvt_pk_bf16_f32 v197, v186, v187
	v_cvt_pk_bf16_f32 v198, v188, v189
	v_cvt_pk_bf16_f32 v199, v190, v191
	v_add_u32_e32 v201, 0xc6000, v248
	global_store_dwordx4 v201, v[196:199], s[48:49] sc0 sc1
	v_pk_mul_f32 v[176:177], v[20:21], v[162:163] op_sel_hi:[1,0]
	v_pk_mul_f32 v[178:179], v[22:23], v[162:163] op_sel_hi:[1,0]
	v_pk_mul_f32 v[180:181], v[16:17], v[162:163] op_sel_hi:[1,0]
	v_pk_mul_f32 v[182:183], v[18:19], v[162:163] op_sel_hi:[1,0]
	v_exp_f32_e32 v176, v176
	v_exp_f32_e32 v177, v177
	v_exp_f32_e32 v178, v178
	v_exp_f32_e32 v179, v179
	v_exp_f32_e32 v180, v180
	v_exp_f32_e32 v181, v181
	v_exp_f32_e32 v182, v182
	v_exp_f32_e32 v183, v183
	v_pk_fma_f32 v[176:177], v[176:177], v[164:165], v[164:165] op_sel_hi:[1,0,0]
	v_pk_fma_f32 v[178:179], v[178:179], v[164:165], v[164:165] op_sel_hi:[1,0,0]
	v_pk_fma_f32 v[180:181], v[180:181], v[164:165], v[164:165] op_sel_hi:[1,0,0]
	v_pk_fma_f32 v[182:183], v[182:183], v[164:165], v[164:165] op_sel_hi:[1,0,0]
	v_rcp_f32_e32 v176, v176
	v_rcp_f32_e32 v177, v177
	v_rcp_f32_e32 v178, v178
	v_rcp_f32_e32 v179, v179
	v_rcp_f32_e32 v180, v180
	v_rcp_f32_e32 v181, v181
	v_rcp_f32_e32 v182, v182
	v_rcp_f32_e32 v183, v183
	v_pk_mul_f32 v[20:21], v[20:21], v[28:29]
	v_pk_mul_f32 v[22:23], v[22:23], v[30:31]
	v_pk_mul_f32 v[16:17], v[16:17], v[24:25]
	v_pk_mul_f32 v[18:19], v[18:19], v[26:27]
	v_pk_mul_f32 v[176:177], v[20:21], v[176:177]
	v_pk_mul_f32 v[178:179], v[22:23], v[178:179]
	v_pk_mul_f32 v[180:181], v[16:17], v[180:181]
	v_pk_mul_f32 v[182:183], v[18:19], v[182:183]
	v_cvt_pk_bf16_f32 v192, v176, v177
	v_cvt_pk_bf16_f32 v193, v178, v179
	v_cvt_pk_bf16_f32 v194, v180, v181
	v_cvt_pk_bf16_f32 v195, v182, v183
	v_add_u32_e32 v200, 0xdc000, v248
	global_store_dwordx4 v200, v[192:195], s[48:49] sc0 sc1
	v_pk_mul_f32 v[184:185], v[4:5], v[166:167] op_sel_hi:[1,0]
	v_pk_mul_f32 v[186:187], v[6:7], v[166:167] op_sel_hi:[1,0]
	v_pk_mul_f32 v[188:189], v[0:1], v[166:167] op_sel_hi:[1,0]
	v_pk_mul_f32 v[190:191], v[2:3], v[166:167] op_sel_hi:[1,0]
	v_exp_f32_e32 v184, v184
	v_exp_f32_e32 v185, v185
	v_exp_f32_e32 v186, v186
	v_exp_f32_e32 v187, v187
	v_exp_f32_e32 v188, v188
	v_exp_f32_e32 v189, v189
	v_exp_f32_e32 v190, v190
	v_exp_f32_e32 v191, v191
	v_pk_fma_f32 v[184:185], v[184:185], v[168:169], v[168:169] op_sel_hi:[1,0,0]
	v_pk_fma_f32 v[186:187], v[186:187], v[168:169], v[168:169] op_sel_hi:[1,0,0]
	v_pk_fma_f32 v[188:189], v[188:189], v[168:169], v[168:169] op_sel_hi:[1,0,0]
	v_pk_fma_f32 v[190:191], v[190:191], v[168:169], v[168:169] op_sel_hi:[1,0,0]
	v_rcp_f32_e32 v184, v184
	v_rcp_f32_e32 v185, v185
	v_rcp_f32_e32 v186, v186
	v_rcp_f32_e32 v187, v187
	v_rcp_f32_e32 v188, v188
	v_rcp_f32_e32 v189, v189
	v_rcp_f32_e32 v190, v190
	v_rcp_f32_e32 v191, v191
	v_pk_mul_f32 v[4:5], v[4:5], v[12:13]
	v_pk_mul_f32 v[6:7], v[6:7], v[14:15]
	v_pk_mul_f32 v[0:1], v[0:1], v[8:9]
	v_pk_mul_f32 v[2:3], v[2:3], v[10:11]
	v_pk_mul_f32 v[184:185], v[4:5], v[184:185]
	v_pk_mul_f32 v[186:187], v[6:7], v[186:187]
	v_pk_mul_f32 v[188:189], v[0:1], v[188:189]
	v_pk_mul_f32 v[190:191], v[2:3], v[190:191]
	v_cvt_pk_bf16_f32 v196, v184, v185
	v_cvt_pk_bf16_f32 v197, v186, v187
	v_cvt_pk_bf16_f32 v198, v188, v189
	v_cvt_pk_bf16_f32 v199, v190, v191
	v_add_u32_e32 v201, 0xf2000, v248
	global_store_dwordx4 v201, v[196:199], s[48:49] sc0 sc1

; __device__ __forceinline__ float rs_from(const float* p, int n4, float inv_n) {
;     float s = 0.f;
;     for (int i = 0; i < n4; ++i) { const f32x4 v = *(const f32x4*)(p + 4 * i); s += (v[0] + v[1]) + (v[2] + v[3]); }
;     return rsqrtf(s * inv_n + EPS);
;     __device__ __forceinline__ void operator()(AccRef acc, const pg8::Unit& u, int wr, int wc, int fr, int fq) const {
;         const int row0 = u.pm * 256 + wr * 64 + fr, col0 = u.pn * 128 + wc * 32 + 8 * fq;
; #pragma unroll
;         for (int ai = 0; ai < 2; ++ai)
; #pragma unroll
;             for (int m = 0; m < 4; ++m) {
;                 const int row = row0 + ai * 128 + m * 16;
;                 const float rs = rs_from(ssp + (size_t)row * 16, 4, 1.0f / 1024.0f);
;                 f32x4 o[2];
; #pragma unroll
;                 for (int n = 0; n < 2; ++n)
; #pragma unroll
;                     for (int j = 0; j < 4; ++j) {
;                         const float g = acc[ai][0][m][n][j] * rs, up = acc[ai][1][m][n][j] * rs;
;                         o[n][j] = g * __builtin_amdgcn_rcpf(1.0f + __expf(-g)) * up;
;                     }
;                 *(u32x4*)(act + (size_t)row * FF + col0) = pack8(o[0], o[1]);
.LBB0_1320:
.Lswi_beg1:
	v_add_u32_e32 v249, 0x2000, v247
	global_load_dwordx4 v[154:157], v249, s[46:47]
	global_load_dwordx4 v[158:161], v249, s[46:47] offset:1024
	global_load_dwordx4 v[162:165], v249, s[46:47] offset:2048
	global_load_dwordx4 v[166:169], v249, s[46:47] offset:3072
	v_mbcnt_lo_u32_b32 v170, -1, 0
	v_mbcnt_hi_u32_b32 v170, -1, v170
	v_xor_b32_e32 v171, 16, v170
	v_xor_b32_e32 v172, 32, v170
	v_lshlrev_b32_e32 v171, 2, v171
	v_lshlrev_b32_e32 v172, 2, v172
	v_lshl_or_b32 v173, s61, 7, v148
	v_lshlrev_b32_e32 v173, 1, v173
	v_mad_u32_u24 v248, v246, s57, v173
	s_waitcnt vmcnt(12)
	v_add_f32_e32 v230, v230, v231
	v_add_f32_e32 v232, v232, v233
	v_add_f32_e32 v234, v234, v235
	v_add_f32_e32 v236, v236, v237
	v_add_f32_e32 v238, v238, v239
	v_add_f32_e32 v240, v240, v241
	v_add_f32_e32 v242, v242, v243
	v_add_f32_e32 v244, v244, v245
	v_add_f32_e32 v230, v230, v232
	v_add_f32_e32 v234, v234, v236
	v_add_f32_e32 v238, v238, v240
	v_add_f32_e32 v242, v242, v244
	ds_bpermute_b32 v231, v171, v230
	ds_bpermute_b32 v235, v171, v234
	ds_bpermute_b32 v239, v171, v238
	ds_bpermute_b32 v243, v171, v242
	s_waitcnt lgkmcnt(0)
	v_add_f32_e32 v230, v230, v231
	v_add_f32_e32 v234, v234, v235
	v_add_f32_e32 v238, v238, v239
	v_add_f32_e32 v242, v242, v243
	ds_bpermute_b32 v231, v172, v230
	ds_bpermute_b32 v235, v172, v234
	ds_bpermute_b32 v239, v172, v238
	ds_bpermute_b32 v243, v172, v242
	s_waitcnt lgkmcnt(0)
	v_add_f32_e32 v230, v230, v231
	v_add_f32_e32 v234, v234, v235
	v_add_f32_e32 v238, v238, v239
	v_add_f32_e32 v242, v242, v243
	v_fmamk_f32 v232, v230, 0x3a800000, v152
	v_fmamk_f32 v236, v234, 0x3a800000, v152
	v_fmamk_f32 v240, v238, 0x3a800000, v152
	v_fmamk_f32 v244, v242, 0x3a800000, v152
	v_rsq_f32_e32 v230, v232
	v_rsq_f32_e32 v234, v236
	v_rsq_f32_e32 v238, v240
	v_rsq_f32_e32 v242, v244
	s_nop 0
	v_mul_f32_e32 v230, 0xbfb8aa3b, v230
	v_mul_f32_e32 v234, 0xbfb8aa3b, v234
	v_mul_f32_e32 v238, 0xbfb8aa3b, v238
	v_mul_f32_e32 v242, 0xbfb8aa3b, v242
	v_pk_mul_f32 v[176:177], v[116:117], v[230:231] op_sel_hi:[1,0]
	v_pk_mul_f32 v[178:179], v[118:119], v[230:231] op_sel_hi:[1,0]
	v_pk_mul_f32 v[180:181], v[112:113], v[230:231] op_sel_hi:[1,0]
	v_pk_mul_f32 v[182:183], v[114:115], v[230:231] op_sel_hi:[1,0]
	v_exp_f32_e32 v176, v176
	v_exp_f32_e32 v177, v177
	v_exp_f32_e32 v178, v178
	v_exp_f32_e32 v179, v179
	v_exp_f32_e32 v180, v180
	v_exp_f32_e32 v181, v181
	v_exp_f32_e32 v182, v182
	v_exp_f32_e32 v183, v183
	v_pk_fma_f32 v[176:177], v[176:177], v[232:233], v[232:233] op_sel_hi:[1,0,0]
	v_pk_fma_f32 v[178:179], v[178:179], v[232:233], v[232:233] op_sel_hi:[1,0,0]
	v_pk_fma_f32 v[180:181], v[180:181], v[232:233], v[232:233] op_sel_hi:[1,0,0]
	v_pk_fma_f32 v[182:183], v[182:183], v[232:233], v[232:233] op_sel_hi:[1,0,0]
	v_rcp_f32_e32 v176, v176
	v_rcp_f32_e32 v177, v177
	v_rcp_f32_e32 v178, v178
	v_rcp_f32_e32 v179, v179
	v_rcp_f32_e32 v180, v180
	v_rcp_f32_e32 v181, v181
	v_rcp_f32_e32 v182, v182
	v_rcp_f32_e32 v183, v183
	v_pk_mul_f32 v[116:117], v[116:117], v[124:125]
	v_pk_mul_f32 v[118:119], v[118:119], v[126:127]
	v_pk_mul_f32 v[112:113], v[112:113], v[120:121]
	v_pk_mul_f32 v[114:115], v[114:115], v[122:123]
	v_pk_mul_f32 v[176:177], v[116:117], v[176:177]
	v_pk_mul_f32 v[178:179], v[118:119], v[178:179]
	v_pk_mul_f32 v[180:181], v[112:113], v[180:181]
	v_pk_mul_f32 v[182:183], v[114:115], v[182:183]
	v_cvt_pk_bf16_f32 v192, v176, v177
	v_cvt_pk_bf16_f32 v193, v178, v179
	v_cvt_pk_bf16_f32 v194, v180, v181
	v_cvt_pk_bf16_f32 v195, v182, v183
	v_mov_b32_e32 v200, v248
	global_store_dwordx4 v200, v[192:195], s[48:49] sc0 sc1
	v_pk_mul_f32 v[184:185], v[100:101], v[234:235] op_sel_hi:[1,0]
	v_pk_mul_f32 v[186:187], v[102:103], v[234:235] op_sel_hi:[1,0]
	v_pk_mul_f32 v[188:189], v[96:97], v[234:235] op_sel_hi:[1,0]
	v_pk_mul_f32 v[190:191], v[98:99], v[234:235] op_sel_hi:[1,0]
	v_exp_f32_e32 v184, v184
	v_exp_f32_e32 v185, v185
	v_exp_f32_e32 v186, v186
	v_exp_f32_e32 v187, v187
	v_exp_f32_e32 v188, v188
	v_exp_f32_e32 v189, v189
	v_exp_f32_e32 v190, v190
	v_exp_f32_e32 v191, v191
	v_pk_fma_f32 v[184:185], v[184:185], v[236:237], v[236:237] op_sel_hi:[1,0,0]
	v_pk_fma_f32 v[186:187], v[186:187], v[236:237], v[236:237] op_sel_hi:[1,0,0]
	v_pk_fma_f32 v[188:189], v[188:189], v[236:237], v[236:237] op_sel_hi:[1,0,0]
	v_pk_fma_f32 v[190:191], v[190:191], v[236:237], v[236:237] op_sel_hi:[1,0,0]
	v_rcp_f32_e32 v184, v184
	v_rcp_f32_e32 v185, v185
	v_rcp_f32_e32 v186, v186
	v_rcp_f32_e32 v187, v187
	v_rcp_f32_e32 v188, v188
	v_rcp_f32_e32 v189, v189
	v_rcp_f32_e32 v190, v190
	v_rcp_f32_e32 v191, v191
	v_pk_mul_f32 v[100:101], v[100:101], v[108:109]
	v_pk_mul_f32 v[102:103], v[102:103], v[110:111]
	v_pk_mul_f32 v[96:97], v[96:97], v[104:105]
	v_pk_mul_f32 v[98:99], v[98:99], v[106:107]
	v_pk_mul_f32 v[184:185], v[100:101], v[184:185]
	v_pk_mul_f32 v[186:187], v[102:103], v[186:187]
	v_pk_mul_f32 v[188:189], v[96:97], v[188:189]
	v_pk_mul_f32 v[190:191], v[98:99], v[190:191]
	v_cvt_pk_bf16_f32 v196, v184, v185
	v_cvt_pk_bf16_f32 v197, v186, v187
	v_cvt_pk_bf16_f32 v198, v188, v189
	v_cvt_pk_bf16_f32 v199, v190, v191
	v_add_u32_e32 v201, 0x16000, v248
	global_store_dwordx4 v201, v[196:199], s[48:49] sc0 sc1
	v_pk_mul_f32 v[176:177], v[84:85], v[238:239] op_sel_hi:[1,0]
	v_pk_mul_f32 v[178:179], v[86:87], v[238:239] op_sel_hi:[1,0]
	v_pk_mul_f32 v[180:181], v[80:81], v[238:239] op_sel_hi:[1,0]
	v_pk_mul_f32 v[182:183], v[82:83], v[238:239] op_sel_hi:[1,0]
	v_exp_f32_e32 v176, v176
	v_exp_f32_e32 v177, v177
	v_exp_f32_e32 v178, v178
	v_exp_f32_e32 v179, v179
	v_exp_f32_e32 v180, v180
	v_exp_f32_e32 v181, v181
	v_exp_f32_e32 v182, v182
; __device__ __forceinline__ float rs_from(const float* p, int n4, float inv_n) {
;     float s = 0.f;
;     for (int i = 0; i < n4; ++i) { const f32x4 v = *(const f32x4*)(p + 4 * i); s += (v[0] + v[1]) + (v[2] + v[3]); }
;     return rsqrtf(s * inv_n + EPS);
;     __device__ __forceinline__ void operator()(AccRef acc, const pg8::Unit& u, int wr, int wc, int fr, int fq) const {
;         const int row0 = u.pm * 256 + wr * 64 + fr, col0 = u.pn * 128 + wc * 32 + 8 * fq;
; #pragma unroll
;         for (int ai = 0; ai < 2; ++ai)
; #pragma unroll
;             for (int m = 0; m < 4; ++m) {
;                 const int row = row0 + ai * 128 + m * 16;
;                 const float rs = rs_from(ssp + (size_t)row * 16, 4, 1.0f / 1024.0f);
;                 f32x4 o[2];
; #pragma unroll
;                 for (int n = 0; n < 2; ++n)
; #pragma unroll
;                     for (int j = 0; j < 4; ++j) {
;                         const float g = acc[ai][0][m][n][j] * rs, up = acc[ai][1][m][n][j] * rs;
;                         o[n][j] = g * __builtin_amdgcn_rcpf(1.0f + __expf(-g)) * up;
;                     }
;                 *(u32x4*)(act + (size_t)row * FF + col0) = pack8(o[0], o[1]);
	v_exp_f32_e32 v183, v183
	v_pk_fma_f32 v[176:177], v[176:177], v[240:241], v[240:241] op_sel_hi:[1,0,0]
	v_pk_fma_f32 v[178:179], v[178:179], v[240:241], v[240:241] op_sel_hi:[1,0,0]
	v_pk_fma_f32 v[180:181], v[180:181], v[240:241], v[240:241] op_sel_hi:[1,0,0]
	v_pk_fma_f32 v[182:183], v[182:183], v[240:241], v[240:241] op_sel_hi:[1,0,0]
	v_rcp_f32_e32 v176, v176
	v_rcp_f32_e32 v177, v177
	v_rcp_f32_e32 v178, v178
	v_rcp_f32_e32 v179, v179
	v_rcp_f32_e32 v180, v180
	v_rcp_f32_e32 v181, v181
	v_rcp_f32_e32 v182, v182
	v_rcp_f32_e32 v183, v183
	v_pk_mul_f32 v[84:85], v[84:85], v[92:93]
	v_pk_mul_f32 v[86:87], v[86:87], v[94:95]
	v_pk_mul_f32 v[80:81], v[80:81], v[88:89]
	v_pk_mul_f32 v[82:83], v[82:83], v[90:91]
	v_pk_mul_f32 v[176:177], v[84:85], v[176:177]
	v_pk_mul_f32 v[178:179], v[86:87], v[178:179]
	v_pk_mul_f32 v[180:181], v[80:81], v[180:181]
	v_pk_mul_f32 v[182:183], v[82:83], v[182:183]
	v_cvt_pk_bf16_f32 v192, v176, v177
	v_cvt_pk_bf16_f32 v193, v178, v179
	v_cvt_pk_bf16_f32 v194, v180, v181
	v_cvt_pk_bf16_f32 v195, v182, v183
	v_add_u32_e32 v200, 0x2c000, v248
	global_store_dwordx4 v200, v[192:195], s[48:49] sc0 sc1
	v_pk_mul_f32 v[184:185], v[68:69], v[242:243] op_sel_hi:[1,0]
	v_pk_mul_f32 v[186:187], v[70:71], v[242:243] op_sel_hi:[1,0]
	v_pk_mul_f32 v[188:189], v[64:65], v[242:243] op_sel_hi:[1,0]
	v_pk_mul_f32 v[190:191], v[66:67], v[242:243] op_sel_hi:[1,0]
	v_exp_f32_e32 v184, v184
	v_exp_f32_e32 v185, v185
	v_exp_f32_e32 v186, v186
	v_exp_f32_e32 v187, v187
	v_exp_f32_e32 v188, v188
	v_exp_f32_e32 v189, v189
	v_exp_f32_e32 v190, v190
	v_exp_f32_e32 v191, v191
	v_pk_fma_f32 v[184:185], v[184:185], v[244:245], v[244:245] op_sel_hi:[1,0,0]
	v_pk_fma_f32 v[186:187], v[186:187], v[244:245], v[244:245] op_sel_hi:[1,0,0]
	v_pk_fma_f32 v[188:189], v[188:189], v[244:245], v[244:245] op_sel_hi:[1,0,0]
	v_pk_fma_f32 v[190:191], v[190:191], v[244:245], v[244:245] op_sel_hi:[1,0,0]
	v_rcp_f32_e32 v184, v184
	v_rcp_f32_e32 v185, v185
	v_rcp_f32_e32 v186, v186
	v_rcp_f32_e32 v187, v187
	v_rcp_f32_e32 v188, v188
	v_rcp_f32_e32 v189, v189
	v_rcp_f32_e32 v190, v190
	v_rcp_f32_e32 v191, v191
	v_pk_mul_f32 v[68:69], v[68:69], v[76:77]
	v_pk_mul_f32 v[70:71], v[70:71], v[78:79]
	v_pk_mul_f32 v[64:65], v[64:65], v[72:73]
	v_pk_mul_f32 v[66:67], v[66:67], v[74:75]
	v_pk_mul_f32 v[184:185], v[68:69], v[184:185]
	v_pk_mul_f32 v[186:187], v[70:71], v[186:187]
	v_pk_mul_f32 v[188:189], v[64:65], v[188:189]
	v_pk_mul_f32 v[190:191], v[66:67], v[190:191]
	v_cvt_pk_bf16_f32 v196, v184, v185
	v_cvt_pk_bf16_f32 v197, v186, v187
	v_cvt_pk_bf16_f32 v198, v188, v189
	v_cvt_pk_bf16_f32 v199, v190, v191
	v_add_u32_e32 v201, 0x42000, v248
	global_store_dwordx4 v201, v[196:199], s[48:49] sc0 sc1
	s_waitcnt vmcnt(4)
	v_add_f32_e32 v154, v154, v155
	v_add_f32_e32 v156, v156, v157
	v_add_f32_e32 v158, v158, v159
	v_add_f32_e32 v160, v160, v161
	v_add_f32_e32 v162, v162, v163
	v_add_f32_e32 v164, v164, v165
	v_add_f32_e32 v166, v166, v167
	v_add_f32_e32 v168, v168, v169
	v_add_f32_e32 v154, v154, v156
	v_add_f32_e32 v158, v158, v160
	v_add_f32_e32 v162, v162, v164
	v_add_f32_e32 v166, v166, v168
	ds_bpermute_b32 v155, v171, v154
	ds_bpermute_b32 v159, v171, v158
	ds_bpermute_b32 v163, v171, v162
	ds_bpermute_b32 v167, v171, v166
	s_waitcnt lgkmcnt(0)
	v_add_f32_e32 v154, v154, v155
	v_add_f32_e32 v158, v158, v159
	v_add_f32_e32 v162, v162, v163
	v_add_f32_e32 v166, v166, v167
	ds_bpermute_b32 v155, v172, v154
	ds_bpermute_b32 v159, v172, v158
	ds_bpermute_b32 v163, v172, v162
	ds_bpermute_b32 v167, v172, v166
	s_waitcnt lgkmcnt(0)
; __device__ __forceinline__ float rs_from(const float* p, int n4, float inv_n) {
;     float s = 0.f;
;     for (int i = 0; i < n4; ++i) { const f32x4 v = *(const f32x4*)(p + 4 * i); s += (v[0] + v[1]) + (v[2] + v[3]); }
;     return rsqrtf(s * inv_n + EPS);
;     __device__ __forceinline__ void operator()(AccRef acc, const pg8::Unit& u, int wr, int wc, int fr, int fq) const {
;         const int row0 = u.pm * 256 + wr * 64 + fr, col0 = u.pn * 128 + wc * 32 + 8 * fq;
; #pragma unroll
;         for (int ai = 0; ai < 2; ++ai)
; #pragma unroll
;             for (int m = 0; m < 4; ++m) {
;                 const int row = row0 + ai * 128 + m * 16;
;                 const float rs = rs_from(ssp + (size_t)row * 16, 4, 1.0f / 1024.0f);
;                 f32x4 o[2];
; #pragma unroll
;                 for (int n = 0; n < 2; ++n)
; #pragma unroll
;                     for (int j = 0; j < 4; ++j) {
;                         const float g = acc[ai][0][m][n][j] * rs, up = acc[ai][1][m][n][j] * rs;
;                         o[n][j] = g * __builtin_amdgcn_rcpf(1.0f + __expf(-g)) * up;
;                     }
;                 *(u32x4*)(act + (size_t)row * FF + col0) = pack8(o[0], o[1]);
	v_add_f32_e32 v154, v154, v155
	v_add_f32_e32 v158, v158, v159
	v_add_f32_e32 v162, v162, v163
	v_add_f32_e32 v166, v166, v167
	v_fmamk_f32 v156, v154, 0x3a800000, v152
	v_fmamk_f32 v160, v158, 0x3a800000, v152
	v_fmamk_f32 v164, v162, 0x3a800000, v152
	v_fmamk_f32 v168, v166, 0x3a800000, v152
	v_rsq_f32_e32 v154, v156
	v_rsq_f32_e32 v158, v160
	v_rsq_f32_e32 v162, v164
	v_rsq_f32_e32 v166, v168
	s_nop 0
	v_mul_f32_e32 v154, 0xbfb8aa3b, v154
	v_mul_f32_e32 v158, 0xbfb8aa3b, v158
	v_mul_f32_e32 v162, 0xbfb8aa3b, v162
	v_mul_f32_e32 v166, 0xbfb8aa3b, v166
	v_pk_mul_f32 v[176:177], v[52:53], v[154:155] op_sel_hi:[1,0]
	v_pk_mul_f32 v[178:179], v[54:55], v[154:155] op_sel_hi:[1,0]
	v_pk_mul_f32 v[180:181], v[48:49], v[154:155] op_sel_hi:[1,0]
	v_pk_mul_f32 v[182:183], v[50:51], v[154:155] op_sel_hi:[1,0]
	v_exp_f32_e32 v176, v176
	v_exp_f32_e32 v177, v177
	v_exp_f32_e32 v178, v178
	v_exp_f32_e32 v179, v179
	v_exp_f32_e32 v180, v180
	v_exp_f32_e32 v181, v181
	v_exp_f32_e32 v182, v182
	v_exp_f32_e32 v183, v183
	v_pk_fma_f32 v[176:177], v[176:177], v[156:157], v[156:157] op_sel_hi:[1,0,0]
	v_pk_fma_f32 v[178:179], v[178:179], v[156:157], v[156:157] op_sel_hi:[1,0,0]
	v_pk_fma_f32 v[180:181], v[180:181], v[156:157], v[156:157] op_sel_hi:[1,0,0]
	v_pk_fma_f32 v[182:183], v[182:183], v[156:157], v[156:157] op_sel_hi:[1,0,0]
	v_rcp_f32_e32 v176, v176
	v_rcp_f32_e32 v177, v177
	v_rcp_f32_e32 v178, v178
	v_rcp_f32_e32 v179, v179
	v_rcp_f32_e32 v180, v180
	v_rcp_f32_e32 v181, v181
	v_rcp_f32_e32 v182, v182
	v_rcp_f32_e32 v183, v183
	v_pk_mul_f32 v[52:53], v[52:53], v[60:61]
	v_pk_mul_f32 v[54:55], v[54:55], v[62:63]
	v_pk_mul_f32 v[48:49], v[48:49], v[56:57]
	v_pk_mul_f32 v[50:51], v[50:51], v[58:59]
	v_pk_mul_f32 v[176:177], v[52:53], v[176:177]
	v_pk_mul_f32 v[178:179], v[54:55], v[178:179]
	v_pk_mul_f32 v[180:181], v[48:49], v[180:181]
	v_pk_mul_f32 v[182:183], v[50:51], v[182:183]
	v_cvt_pk_bf16_f32 v192, v176, v177
	v_cvt_pk_bf16_f32 v193, v178, v179
	v_cvt_pk_bf16_f32 v194, v180, v181
	v_cvt_pk_bf16_f32 v195, v182, v183
	v_add_u32_e32 v200, 0xb0000, v248
	global_store_dwordx4 v200, v[192:195], s[48:49] sc0 sc1
	v_pk_mul_f32 v[184:185], v[36:37], v[158:159] op_sel_hi:[1,0]
	v_pk_mul_f32 v[186:187], v[38:39], v[158:159] op_sel_hi:[1,0]
	v_pk_mul_f32 v[188:189], v[32:33], v[158:159] op_sel_hi:[1,0]
	v_pk_mul_f32 v[190:191], v[34:35], v[158:159] op_sel_hi:[1,0]
	v_exp_f32_e32 v184, v184
	v_exp_f32_e32 v185, v185
	v_exp_f32_e32 v186, v186
	v_exp_f32_e32 v187, v187
	v_exp_f32_e32 v188, v188
	v_exp_f32_e32 v189, v189
	v_exp_f32_e32 v190, v190
	v_exp_f32_e32 v191, v191
	v_pk_fma_f32 v[184:185], v[184:185], v[160:161], v[160:161] op_sel_hi:[1,0,0]
	v_pk_fma_f32 v[186:187], v[186:187], v[160:161], v[160:161] op_sel_hi:[1,0,0]
	v_pk_fma_f32 v[188:189], v[188:189], v[160:161], v[160:161] op_sel_hi:[1,0,0]
	v_pk_fma_f32 v[190:191], v[190:191], v[160:161], v[160:161] op_sel_hi:[1,0,0]
	v_rcp_f32_e32 v184, v184
	v_rcp_f32_e32 v185, v185
	v_rcp_f32_e32 v186, v186
	v_rcp_f32_e32 v187, v187
	v_rcp_f32_e32 v188, v188
	v_rcp_f32_e32 v189, v189
	v_rcp_f32_e32 v190, v190
	v_rcp_f32_e32 v191, v191
	v_pk_mul_f32 v[36:37], v[36:37], v[44:45]
	v_pk_mul_f32 v[38:39], v[38:39], v[46:47]
	v_pk_mul_f32 v[32:33], v[32:33], v[40:41]
	v_pk_mul_f32 v[34:35], v[34:35], v[42:43]
	v_pk_mul_f32 v[184:185], v[36:37], v[184:185]
	v_pk_mul_f32 v[186:187], v[38:39], v[186:187]
	v_pk_mul_f32 v[188:189], v[32:33], v[188:189]
	v_pk_mul_f32 v[190:191], v[34:35], v[190:191]
	v_cvt_pk_bf16_f32 v196, v184, v185
	v_cvt_pk_bf16_f32 v197, v186, v187
	v_cvt_pk_bf16_f32 v198, v188, v189
	v_cvt_pk_bf16_f32 v199, v190, v191
	v_add_u32_e32 v201, 0xc6000, v248
	global_store_dwordx4 v201, v[196:199], s[48:49] sc0 sc1
	v_pk_mul_f32 v[176:177], v[20:21], v[162:163] op_sel_hi:[1,0]
	v_pk_mul_f32 v[178:179], v[22:23], v[162:163] op_sel_hi:[1,0]
	v_pk_mul_f32 v[180:181], v[16:17], v[162:163] op_sel_hi:[1,0]
	v_pk_mul_f32 v[182:183], v[18:19], v[162:163] op_sel_hi:[1,0]
	v_exp_f32_e32 v176, v176
	v_exp_f32_e32 v177, v177
	v_exp_f32_e32 v178, v178
	v_exp_f32_e32 v179, v179
	v_exp_f32_e32 v180, v180
	v_exp_f32_e32 v181, v181
	v_exp_f32_e32 v182, v182
	v_exp_f32_e32 v183, v183
	v_pk_fma_f32 v[176:177], v[176:177], v[164:165], v[164:165] op_sel_hi:[1,0,0]
	v_pk_fma_f32 v[178:179], v[178:179], v[164:165], v[164:165] op_sel_hi:[1,0,0]
	v_pk_fma_f32 v[180:181], v[180:181], v[164:165], v[164:165] op_sel_hi:[1,0,0]
	v_pk_fma_f32 v[182:183], v[182:183], v[164:165], v[164:165] op_sel_hi:[1,0,0]
	v_rcp_f32_e32 v176, v176
	v_rcp_f32_e32 v177, v177
	v_rcp_f32_e32 v178, v178
	v_rcp_f32_e32 v179, v179
	v_rcp_f32_e32 v180, v180
	v_rcp_f32_e32 v181, v181
	v_rcp_f32_e32 v182, v182
	v_rcp_f32_e32 v183, v183
	v_pk_mul_f32 v[20:21], v[20:21], v[28:29]
	v_pk_mul_f32 v[22:23], v[22:23], v[30:31]
	v_pk_mul_f32 v[16:17], v[16:17], v[24:25]
	v_pk_mul_f32 v[18:19], v[18:19], v[26:27]
	v_pk_mul_f32 v[176:177], v[20:21], v[176:177]
	v_pk_mul_f32 v[178:179], v[22:23], v[178:179]
	v_pk_mul_f32 v[180:181], v[16:17], v[180:181]
	v_pk_mul_f32 v[182:183], v[18:19], v[182:183]
	v_cvt_pk_bf16_f32 v192, v176, v177
	v_cvt_pk_bf16_f32 v193, v178, v179
	v_cvt_pk_bf16_f32 v194, v180, v181
	v_cvt_pk_bf16_f32 v195, v182, v183
	v_add_u32_e32 v200, 0xdc000, v248
	global_store_dwordx4 v200, v[192:195], s[48:49] sc0 sc1
	v_pk_mul_f32 v[184:185], v[4:5], v[166:167] op_sel_hi:[1,0]
	v_pk_mul_f32 v[186:187], v[6:7], v[166:167] op_sel_hi:[1,0]
	v_pk_mul_f32 v[188:189], v[0:1], v[166:167] op_sel_hi:[1,0]
	v_pk_mul_f32 v[190:191], v[2:3], v[166:167] op_sel_hi:[1,0]
	v_exp_f32_e32 v184, v184
	v_exp_f32_e32 v185, v185
	v_exp_f32_e32 v186, v186
	v_exp_f32_e32 v187, v187
	v_exp_f32_e32 v188, v188
	v_exp_f32_e32 v189, v189
	v_exp_f32_e32 v190, v190
	v_exp_f32_e32 v191, v191
	v_pk_fma_f32 v[184:185], v[184:185], v[168:169], v[168:169] op_sel_hi:[1,0,0]
	v_pk_fma_f32 v[186:187], v[186:187], v[168:169], v[168:169] op_sel_hi:[1,0,0]
	v_pk_fma_f32 v[188:189], v[188:189], v[168:169], v[168:169] op_sel_hi:[1,0,0]
	v_pk_fma_f32 v[190:191], v[190:191], v[168:169], v[168:169] op_sel_hi:[1,0,0]
	v_rcp_f32_e32 v184, v184
	v_rcp_f32_e32 v185, v185
	v_rcp_f32_e32 v186, v186
	v_rcp_f32_e32 v187, v187
	v_rcp_f32_e32 v188, v188
	v_rcp_f32_e32 v189, v189
	v_rcp_f32_e32 v190, v190
	v_rcp_f32_e32 v191, v191
	v_pk_mul_f32 v[4:5], v[4:5], v[12:13]
	v_pk_mul_f32 v[6:7], v[6:7], v[14:15]
	v_pk_mul_f32 v[0:1], v[0:1], v[8:9]
	v_pk_mul_f32 v[2:3], v[2:3], v[10:11]
	v_pk_mul_f32 v[184:185], v[4:5], v[184:185]
	v_pk_mul_f32 v[186:187], v[6:7], v[186:187]
	v_pk_mul_f32 v[188:189], v[0:1], v[188:189]
	v_pk_mul_f32 v[190:191], v[2:3], v[190:191]
	v_cvt_pk_bf16_f32 v196, v184, v185
	v_cvt_pk_bf16_f32 v197, v186, v187
	v_cvt_pk_bf16_f32 v198, v188, v189
	v_cvt_pk_bf16_f32 v199, v190, v191
	v_add_u32_e32 v201, 0xf2000, v248
	global_store_dwordx4 v201, v[196:199], s[48:49] sc0 sc1

; __device__ __forceinline__ float rs_from(const float* p, int n4, float inv_n) {
;     float s = 0.f;
;     for (int i = 0; i < n4; ++i) { const f32x4 v = *(const f32x4*)(p + 4 * i); s += (v[0] + v[1]) + (v[2] + v[3]); }
;     return rsqrtf(s * inv_n + EPS);
;     __device__ __forceinline__ void operator()(AccRef acc, const pg8::Unit& u, int wr, int wc, int fr, int fq) const {
;         const int row0 = u.pm * 256 + wr * 64 + fr, col0 = u.pn * 128 + wc * 32 + 8 * fq;
; #pragma unroll
;         for (int ai = 0; ai < 2; ++ai)
; #pragma unroll
;             for (int m = 0; m < 4; ++m) {
;                 const int row = row0 + ai * 128 + m * 16;
;                 const float rs = rs_from(ssp + (size_t)row * 16, 4, 1.0f / 1024.0f);
;                 f32x4 o[2];
; #pragma unroll
;                 for (int n = 0; n < 2; ++n)
; #pragma unroll
;                     for (int j = 0; j < 4; ++j) {
;                         const float g = acc[ai][0][m][n][j] * rs, up = acc[ai][1][m][n][j] * rs;
;                         o[n][j] = g * __builtin_amdgcn_rcpf(1.0f + __expf(-g)) * up;
;                     }
;                 *(u32x4*)(act + (size_t)row * FF + col0) = pack8(o[0], o[1]);
.LBB0_2484:
.Lswi_beg3:
	v_add_u32_e32 v249, 0x2000, v247
	global_load_dwordx4 v[154:157], v249, s[46:47]
	global_load_dwordx4 v[158:161], v249, s[46:47] offset:1024
	global_load_dwordx4 v[162:165], v249, s[46:47] offset:2048
	global_load_dwordx4 v[166:169], v249, s[46:47] offset:3072
	v_mbcnt_lo_u32_b32 v170, -1, 0
	v_mbcnt_hi_u32_b32 v170, -1, v170
	v_xor_b32_e32 v171, 16, v170
	v_xor_b32_e32 v172, 32, v170
	v_lshlrev_b32_e32 v171, 2, v171
	v_lshlrev_b32_e32 v172, 2, v172
	v_lshl_or_b32 v173, s59, 7, v148
	v_lshlrev_b32_e32 v173, 1, v173
	v_mad_u32_u24 v248, v246, s51, v173
	s_waitcnt vmcnt(12)
	v_add_f32_e32 v230, v230, v231
	v_add_f32_e32 v232, v232, v233
	v_add_f32_e32 v234, v234, v235
	v_add_f32_e32 v236, v236, v237
	v_add_f32_e32 v238, v238, v239
	v_add_f32_e32 v240, v240, v241
	v_add_f32_e32 v242, v242, v243
	v_add_f32_e32 v244, v244, v245
	v_add_f32_e32 v230, v230, v232
	v_add_f32_e32 v234, v234, v236
	v_add_f32_e32 v238, v238, v240
	v_add_f32_e32 v242, v242, v244
	ds_bpermute_b32 v231, v171, v230
	ds_bpermute_b32 v235, v171, v234
	ds_bpermute_b32 v239, v171, v238
	ds_bpermute_b32 v243, v171, v242
	s_waitcnt lgkmcnt(0)
	v_add_f32_e32 v230, v230, v231
	v_add_f32_e32 v234, v234, v235
	v_add_f32_e32 v238, v238, v239
	v_add_f32_e32 v242, v242, v243
	ds_bpermute_b32 v231, v172, v230
	ds_bpermute_b32 v235, v172, v234
	ds_bpermute_b32 v239, v172, v238
	ds_bpermute_b32 v243, v172, v242
	s_waitcnt lgkmcnt(0)
	v_add_f32_e32 v230, v230, v231
	v_add_f32_e32 v234, v234, v235
	v_add_f32_e32 v238, v238, v239
	v_add_f32_e32 v242, v242, v243
	v_fmamk_f32 v232, v230, 0x3a800000, v152
	v_fmamk_f32 v236, v234, 0x3a800000, v152
	v_fmamk_f32 v240, v238, 0x3a800000, v152
	v_fmamk_f32 v244, v242, 0x3a800000, v152
	v_rsq_f32_e32 v230, v232
	v_rsq_f32_e32 v234, v236
	v_rsq_f32_e32 v238, v240
	v_rsq_f32_e32 v242, v244
	s_nop 0
	v_mul_f32_e32 v230, 0xbfb8aa3b, v230
	v_mul_f32_e32 v234, 0xbfb8aa3b, v234
	v_mul_f32_e32 v238, 0xbfb8aa3b, v238
	v_mul_f32_e32 v242, 0xbfb8aa3b, v242
	v_pk_mul_f32 v[176:177], v[116:117], v[230:231] op_sel_hi:[1,0]
	v_pk_mul_f32 v[178:179], v[118:119], v[230:231] op_sel_hi:[1,0]
	v_pk_mul_f32 v[180:181], v[112:113], v[230:231] op_sel_hi:[1,0]
	v_pk_mul_f32 v[182:183], v[114:115], v[230:231] op_sel_hi:[1,0]
	v_exp_f32_e32 v176, v176
	v_exp_f32_e32 v177, v177
	v_exp_f32_e32 v178, v178
	v_exp_f32_e32 v179, v179
	v_exp_f32_e32 v180, v180
	v_exp_f32_e32 v181, v181
	v_exp_f32_e32 v182, v182
	v_exp_f32_e32 v183, v183
	v_pk_fma_f32 v[176:177], v[176:177], v[232:233], v[232:233] op_sel_hi:[1,0,0]
	v_pk_fma_f32 v[178:179], v[178:179], v[232:233], v[232:233] op_sel_hi:[1,0,0]
	v_pk_fma_f32 v[180:181], v[180:181], v[232:233], v[232:233] op_sel_hi:[1,0,0]
	v_pk_fma_f32 v[182:183], v[182:183], v[232:233], v[232:233] op_sel_hi:[1,0,0]
	v_rcp_f32_e32 v176, v176
	v_rcp_f32_e32 v177, v177
	v_rcp_f32_e32 v178, v178
	v_rcp_f32_e32 v179, v179
	v_rcp_f32_e32 v180, v180
	v_rcp_f32_e32 v181, v181
	v_rcp_f32_e32 v182, v182
	v_rcp_f32_e32 v183, v183
	v_pk_mul_f32 v[116:117], v[116:117], v[124:125]
	v_pk_mul_f32 v[118:119], v[118:119], v[126:127]
	v_pk_mul_f32 v[112:113], v[112:113], v[120:121]
	v_pk_mul_f32 v[114:115], v[114:115], v[122:123]
	v_pk_mul_f32 v[176:177], v[116:117], v[176:177]
	v_pk_mul_f32 v[178:179], v[118:119], v[178:179]
	v_pk_mul_f32 v[180:181], v[112:113], v[180:181]
	v_pk_mul_f32 v[182:183], v[114:115], v[182:183]
	v_cvt_pk_bf16_f32 v192, v176, v177
	v_cvt_pk_bf16_f32 v193, v178, v179
	v_cvt_pk_bf16_f32 v194, v180, v181
	v_cvt_pk_bf16_f32 v195, v182, v183
	v_mov_b32_e32 v200, v248
	global_store_dwordx4 v200, v[192:195], s[48:49] sc0 sc1
	v_pk_mul_f32 v[184:185], v[100:101], v[234:235] op_sel_hi:[1,0]
	v_pk_mul_f32 v[186:187], v[102:103], v[234:235] op_sel_hi:[1,0]
	v_pk_mul_f32 v[188:189], v[96:97], v[234:235] op_sel_hi:[1,0]
	v_pk_mul_f32 v[190:191], v[98:99], v[234:235] op_sel_hi:[1,0]
	v_exp_f32_e32 v184, v184
	v_exp_f32_e32 v185, v185
	v_exp_f32_e32 v186, v186
	v_exp_f32_e32 v187, v187
	v_exp_f32_e32 v188, v188
	v_exp_f32_e32 v189, v189
	v_exp_f32_e32 v190, v190
	v_exp_f32_e32 v191, v191
	v_pk_fma_f32 v[184:185], v[184:185], v[236:237], v[236:237] op_sel_hi:[1,0,0]
	v_pk_fma_f32 v[186:187], v[186:187], v[236:237], v[236:237] op_sel_hi:[1,0,0]
	v_pk_fma_f32 v[188:189], v[188:189], v[236:237], v[236:237] op_sel_hi:[1,0,0]
	v_pk_fma_f32 v[190:191], v[190:191], v[236:237], v[236:237] op_sel_hi:[1,0,0]
	v_rcp_f32_e32 v184, v184
	v_rcp_f32_e32 v185, v185
	v_rcp_f32_e32 v186, v186
	v_rcp_f32_e32 v187, v187
	v_rcp_f32_e32 v188, v188
	v_rcp_f32_e32 v189, v189
	v_rcp_f32_e32 v190, v190
	v_rcp_f32_e32 v191, v191
	v_pk_mul_f32 v[100:101], v[100:101], v[108:109]
	v_pk_mul_f32 v[102:103], v[102:103], v[110:111]
	v_pk_mul_f32 v[96:97], v[96:97], v[104:105]
	v_pk_mul_f32 v[98:99], v[98:99], v[106:107]
	v_pk_mul_f32 v[184:185], v[100:101], v[184:185]
	v_pk_mul_f32 v[186:187], v[102:103], v[186:187]
	v_pk_mul_f32 v[188:189], v[96:97], v[188:189]
	v_pk_mul_f32 v[190:191], v[98:99], v[190:191]
	v_cvt_pk_bf16_f32 v196, v184, v185
	v_cvt_pk_bf16_f32 v197, v186, v187
	v_cvt_pk_bf16_f32 v198, v188, v189
	v_cvt_pk_bf16_f32 v199, v190, v191
	v_add_u32_e32 v201, 0x16000, v248
	global_store_dwordx4 v201, v[196:199], s[48:49] sc0 sc1
	v_pk_mul_f32 v[176:177], v[84:85], v[238:239] op_sel_hi:[1,0]
	v_pk_mul_f32 v[178:179], v[86:87], v[238:239] op_sel_hi:[1,0]
	v_pk_mul_f32 v[180:181], v[80:81], v[238:239] op_sel_hi:[1,0]
	v_pk_mul_f32 v[182:183], v[82:83], v[238:239] op_sel_hi:[1,0]
	v_exp_f32_e32 v176, v176
	v_exp_f32_e32 v177, v177
	v_exp_f32_e32 v178, v178
	v_exp_f32_e32 v179, v179
	v_exp_f32_e32 v180, v180
	v_exp_f32_e32 v181, v181
	v_exp_f32_e32 v182, v182
; __device__ __forceinline__ float rs_from(const float* p, int n4, float inv_n) {
;     float s = 0.f;
;     for (int i = 0; i < n4; ++i) { const f32x4 v = *(const f32x4*)(p + 4 * i); s += (v[0] + v[1]) + (v[2] + v[3]); }
;     return rsqrtf(s * inv_n + EPS);
;     __device__ __forceinline__ void operator()(AccRef acc, const pg8::Unit& u, int wr, int wc, int fr, int fq) const {
;         const int row0 = u.pm * 256 + wr * 64 + fr, col0 = u.pn * 128 + wc * 32 + 8 * fq;
; #pragma unroll
;         for (int ai = 0; ai < 2; ++ai)
; #pragma unroll
;             for (int m = 0; m < 4; ++m) {
;                 const int row = row0 + ai * 128 + m * 16;
;                 const float rs = rs_from(ssp + (size_t)row * 16, 4, 1.0f / 1024.0f);
;                 f32x4 o[2];
; #pragma unroll
;                 for (int n = 0; n < 2; ++n)
; #pragma unroll
;                     for (int j = 0; j < 4; ++j) {
;                         const float g = acc[ai][0][m][n][j] * rs, up = acc[ai][1][m][n][j] * rs;
;                         o[n][j] = g * __builtin_amdgcn_rcpf(1.0f + __expf(-g)) * up;
;                     }
;                 *(u32x4*)(act + (size_t)row * FF + col0) = pack8(o[0], o[1]);
	v_exp_f32_e32 v183, v183
	v_pk_fma_f32 v[176:177], v[176:177], v[240:241], v[240:241] op_sel_hi:[1,0,0]
	v_pk_fma_f32 v[178:179], v[178:179], v[240:241], v[240:241] op_sel_hi:[1,0,0]
	v_pk_fma_f32 v[180:181], v[180:181], v[240:241], v[240:241] op_sel_hi:[1,0,0]
	v_pk_fma_f32 v[182:183], v[182:183], v[240:241], v[240:241] op_sel_hi:[1,0,0]
	v_rcp_f32_e32 v176, v176
	v_rcp_f32_e32 v177, v177
	v_rcp_f32_e32 v178, v178
	v_rcp_f32_e32 v179, v179
	v_rcp_f32_e32 v180, v180
	v_rcp_f32_e32 v181, v181
	v_rcp_f32_e32 v182, v182
	v_rcp_f32_e32 v183, v183
	v_pk_mul_f32 v[84:85], v[84:85], v[92:93]
	v_pk_mul_f32 v[86:87], v[86:87], v[94:95]
	v_pk_mul_f32 v[80:81], v[80:81], v[88:89]
	v_pk_mul_f32 v[82:83], v[82:83], v[90:91]
	v_pk_mul_f32 v[176:177], v[84:85], v[176:177]
	v_pk_mul_f32 v[178:179], v[86:87], v[178:179]
	v_pk_mul_f32 v[180:181], v[80:81], v[180:181]
	v_pk_mul_f32 v[182:183], v[82:83], v[182:183]
	v_cvt_pk_bf16_f32 v192, v176, v177
	v_cvt_pk_bf16_f32 v193, v178, v179
	v_cvt_pk_bf16_f32 v194, v180, v181
	v_cvt_pk_bf16_f32 v195, v182, v183
	v_add_u32_e32 v200, 0x2c000, v248
	global_store_dwordx4 v200, v[192:195], s[48:49] sc0 sc1
	v_pk_mul_f32 v[184:185], v[68:69], v[242:243] op_sel_hi:[1,0]
	v_pk_mul_f32 v[186:187], v[70:71], v[242:243] op_sel_hi:[1,0]
	v_pk_mul_f32 v[188:189], v[64:65], v[242:243] op_sel_hi:[1,0]
	v_pk_mul_f32 v[190:191], v[66:67], v[242:243] op_sel_hi:[1,0]
	v_exp_f32_e32 v184, v184
	v_exp_f32_e32 v185, v185
	v_exp_f32_e32 v186, v186
	v_exp_f32_e32 v187, v187
	v_exp_f32_e32 v188, v188
	v_exp_f32_e32 v189, v189
	v_exp_f32_e32 v190, v190
	v_exp_f32_e32 v191, v191
	v_pk_fma_f32 v[184:185], v[184:185], v[244:245], v[244:245] op_sel_hi:[1,0,0]
	v_pk_fma_f32 v[186:187], v[186:187], v[244:245], v[244:245] op_sel_hi:[1,0,0]
	v_pk_fma_f32 v[188:189], v[188:189], v[244:245], v[244:245] op_sel_hi:[1,0,0]
	v_pk_fma_f32 v[190:191], v[190:191], v[244:245], v[244:245] op_sel_hi:[1,0,0]
	v_rcp_f32_e32 v184, v184
	v_rcp_f32_e32 v185, v185
	v_rcp_f32_e32 v186, v186
	v_rcp_f32_e32 v187, v187
	v_rcp_f32_e32 v188, v188
	v_rcp_f32_e32 v189, v189
	v_rcp_f32_e32 v190, v190
	v_rcp_f32_e32 v191, v191
	v_pk_mul_f32 v[68:69], v[68:69], v[76:77]
	v_pk_mul_f32 v[70:71], v[70:71], v[78:79]
	v_pk_mul_f32 v[64:65], v[64:65], v[72:73]
	v_pk_mul_f32 v[66:67], v[66:67], v[74:75]
	v_pk_mul_f32 v[184:185], v[68:69], v[184:185]
	v_pk_mul_f32 v[186:187], v[70:71], v[186:187]
	v_pk_mul_f32 v[188:189], v[64:65], v[188:189]
	v_pk_mul_f32 v[190:191], v[66:67], v[190:191]
	v_cvt_pk_bf16_f32 v196, v184, v185
	v_cvt_pk_bf16_f32 v197, v186, v187
	v_cvt_pk_bf16_f32 v198, v188, v189
	v_cvt_pk_bf16_f32 v199, v190, v191
	v_add_u32_e32 v201, 0x42000, v248
	global_store_dwordx4 v201, v[196:199], s[48:49] sc0 sc1
	s_waitcnt vmcnt(4)
	v_add_f32_e32 v154, v154, v155
	v_add_f32_e32 v156, v156, v157
	v_add_f32_e32 v158, v158, v159
	v_add_f32_e32 v160, v160, v161
	v_add_f32_e32 v162, v162, v163
	v_add_f32_e32 v164, v164, v165
	v_add_f32_e32 v166, v166, v167
	v_add_f32_e32 v168, v168, v169
	v_add_f32_e32 v154, v154, v156
	v_add_f32_e32 v158, v158, v160
	v_add_f32_e32 v162, v162, v164
	v_add_f32_e32 v166, v166, v168
	ds_bpermute_b32 v155, v171, v154
	ds_bpermute_b32 v159, v171, v158
	ds_bpermute_b32 v163, v171, v162
	ds_bpermute_b32 v167, v171, v166
	s_waitcnt lgkmcnt(0)
	v_add_f32_e32 v154, v154, v155
	v_add_f32_e32 v158, v158, v159
	v_add_f32_e32 v162, v162, v163
	v_add_f32_e32 v166, v166, v167
	ds_bpermute_b32 v155, v172, v154
	ds_bpermute_b32 v159, v172, v158
	ds_bpermute_b32 v163, v172, v162
	ds_bpermute_b32 v167, v172, v166
	s_waitcnt lgkmcnt(0)
; __device__ __forceinline__ float rs_from(const float* p, int n4, float inv_n) {
;     float s = 0.f;
;     for (int i = 0; i < n4; ++i) { const f32x4 v = *(const f32x4*)(p + 4 * i); s += (v[0] + v[1]) + (v[2] + v[3]); }
;     return rsqrtf(s * inv_n + EPS);
;     __device__ __forceinline__ void operator()(AccRef acc, const pg8::Unit& u, int wr, int wc, int fr, int fq) const {
;         const int row0 = u.pm * 256 + wr * 64 + fr, col0 = u.pn * 128 + wc * 32 + 8 * fq;
; #pragma unroll
;         for (int ai = 0; ai < 2; ++ai)
; #pragma unroll
;             for (int m = 0; m < 4; ++m) {
;                 const int row = row0 + ai * 128 + m * 16;
;                 const float rs = rs_from(ssp + (size_t)row * 16, 4, 1.0f / 1024.0f);
;                 f32x4 o[2];
; #pragma unroll
;                 for (int n = 0; n < 2; ++n)
; #pragma unroll
;                     for (int j = 0; j < 4; ++j) {
;                         const float g = acc[ai][0][m][n][j] * rs, up = acc[ai][1][m][n][j] * rs;
;                         o[n][j] = g * __builtin_amdgcn_rcpf(1.0f + __expf(-g)) * up;
;                     }
;                 *(u32x4*)(act + (size_t)row * FF + col0) = pack8(o[0], o[1]);
	v_add_f32_e32 v154, v154, v155
	v_add_f32_e32 v158, v158, v159
	v_add_f32_e32 v162, v162, v163
	v_add_f32_e32 v166, v166, v167
	v_fmamk_f32 v156, v154, 0x3a800000, v152
	v_fmamk_f32 v160, v158, 0x3a800000, v152
	v_fmamk_f32 v164, v162, 0x3a800000, v152
	v_fmamk_f32 v168, v166, 0x3a800000, v152
	v_rsq_f32_e32 v154, v156
	v_rsq_f32_e32 v158, v160
	v_rsq_f32_e32 v162, v164
	v_rsq_f32_e32 v166, v168
	s_nop 0
	v_mul_f32_e32 v154, 0xbfb8aa3b, v154
	v_mul_f32_e32 v158, 0xbfb8aa3b, v158
	v_mul_f32_e32 v162, 0xbfb8aa3b, v162
	v_mul_f32_e32 v166, 0xbfb8aa3b, v166
	v_pk_mul_f32 v[176:177], v[52:53], v[154:155] op_sel_hi:[1,0]
	v_pk_mul_f32 v[178:179], v[54:55], v[154:155] op_sel_hi:[1,0]
	v_pk_mul_f32 v[180:181], v[48:49], v[154:155] op_sel_hi:[1,0]
	v_pk_mul_f32 v[182:183], v[50:51], v[154:155] op_sel_hi:[1,0]
	v_exp_f32_e32 v176, v176
	v_exp_f32_e32 v177, v177
	v_exp_f32_e32 v178, v178
	v_exp_f32_e32 v179, v179
	v_exp_f32_e32 v180, v180
	v_exp_f32_e32 v181, v181
	v_exp_f32_e32 v182, v182
	v_exp_f32_e32 v183, v183
	v_pk_fma_f32 v[176:177], v[176:177], v[156:157], v[156:157] op_sel_hi:[1,0,0]
	v_pk_fma_f32 v[178:179], v[178:179], v[156:157], v[156:157] op_sel_hi:[1,0,0]
	v_pk_fma_f32 v[180:181], v[180:181], v[156:157], v[156:157] op_sel_hi:[1,0,0]
	v_pk_fma_f32 v[182:183], v[182:183], v[156:157], v[156:157] op_sel_hi:[1,0,0]
	v_rcp_f32_e32 v176, v176
	v_rcp_f32_e32 v177, v177
	v_rcp_f32_e32 v178, v178
	v_rcp_f32_e32 v179, v179
	v_rcp_f32_e32 v180, v180
	v_rcp_f32_e32 v181, v181
	v_rcp_f32_e32 v182, v182
	v_rcp_f32_e32 v183, v183
	v_pk_mul_f32 v[52:53], v[52:53], v[60:61]
	v_pk_mul_f32 v[54:55], v[54:55], v[62:63]
	v_pk_mul_f32 v[48:49], v[48:49], v[56:57]
	v_pk_mul_f32 v[50:51], v[50:51], v[58:59]
	v_pk_mul_f32 v[176:177], v[52:53], v[176:177]
	v_pk_mul_f32 v[178:179], v[54:55], v[178:179]
	v_pk_mul_f32 v[180:181], v[48:49], v[180:181]
	v_pk_mul_f32 v[182:183], v[50:51], v[182:183]
	v_cvt_pk_bf16_f32 v192, v176, v177
	v_cvt_pk_bf16_f32 v193, v178, v179
	v_cvt_pk_bf16_f32 v194, v180, v181
	v_cvt_pk_bf16_f32 v195, v182, v183
	v_add_u32_e32 v200, 0xb0000, v248
	global_store_dwordx4 v200, v[192:195], s[48:49] sc0 sc1
	v_pk_mul_f32 v[184:185], v[36:37], v[158:159] op_sel_hi:[1,0]
	v_pk_mul_f32 v[186:187], v[38:39], v[158:159] op_sel_hi:[1,0]
	v_pk_mul_f32 v[188:189], v[32:33], v[158:159] op_sel_hi:[1,0]
	v_pk_mul_f32 v[190:191], v[34:35], v[158:159] op_sel_hi:[1,0]
	v_exp_f32_e32 v184, v184
	v_exp_f32_e32 v185, v185
	v_exp_f32_e32 v186, v186
	v_exp_f32_e32 v187, v187
	v_exp_f32_e32 v188, v188
	v_exp_f32_e32 v189, v189
	v_exp_f32_e32 v190, v190
	v_exp_f32_e32 v191, v191
	v_pk_fma_f32 v[184:185], v[184:185], v[160:161], v[160:161] op_sel_hi:[1,0,0]
	v_pk_fma_f32 v[186:187], v[186:187], v[160:161], v[160:161] op_sel_hi:[1,0,0]
	v_pk_fma_f32 v[188:189], v[188:189], v[160:161], v[160:161] op_sel_hi:[1,0,0]
	v_pk_fma_f32 v[190:191], v[190:191], v[160:161], v[160:161] op_sel_hi:[1,0,0]
	v_rcp_f32_e32 v184, v184
	v_rcp_f32_e32 v185, v185
	v_rcp_f32_e32 v186, v186
	v_rcp_f32_e32 v187, v187
	v_rcp_f32_e32 v188, v188
	v_rcp_f32_e32 v189, v189
	v_rcp_f32_e32 v190, v190
	v_rcp_f32_e32 v191, v191
	v_pk_mul_f32 v[36:37], v[36:37], v[44:45]
	v_pk_mul_f32 v[38:39], v[38:39], v[46:47]
	v_pk_mul_f32 v[32:33], v[32:33], v[40:41]
	v_pk_mul_f32 v[34:35], v[34:35], v[42:43]
	v_pk_mul_f32 v[184:185], v[36:37], v[184:185]
	v_pk_mul_f32 v[186:187], v[38:39], v[186:187]
	v_pk_mul_f32 v[188:189], v[32:33], v[188:189]
	v_pk_mul_f32 v[190:191], v[34:35], v[190:191]
	v_cvt_pk_bf16_f32 v196, v184, v185
	v_cvt_pk_bf16_f32 v197, v186, v187
	v_cvt_pk_bf16_f32 v198, v188, v189
	v_cvt_pk_bf16_f32 v199, v190, v191
	v_add_u32_e32 v201, 0xc6000, v248
	global_store_dwordx4 v201, v[196:199], s[48:49] sc0 sc1
	v_pk_mul_f32 v[176:177], v[20:21], v[162:163] op_sel_hi:[1,0]
	v_pk_mul_f32 v[178:179], v[22:23], v[162:163] op_sel_hi:[1,0]
	v_pk_mul_f32 v[180:181], v[16:17], v[162:163] op_sel_hi:[1,0]
	v_pk_mul_f32 v[182:183], v[18:19], v[162:163] op_sel_hi:[1,0]
	v_exp_f32_e32 v176, v176
	v_exp_f32_e32 v177, v177
	v_exp_f32_e32 v178, v178
	v_exp_f32_e32 v179, v179
	v_exp_f32_e32 v180, v180
	v_exp_f32_e32 v181, v181
	v_exp_f32_e32 v182, v182
	v_exp_f32_e32 v183, v183
	v_pk_fma_f32 v[176:177], v[176:177], v[164:165], v[164:165] op_sel_hi:[1,0,0]
	v_pk_fma_f32 v[178:179], v[178:179], v[164:165], v[164:165] op_sel_hi:[1,0,0]
	v_pk_fma_f32 v[180:181], v[180:181], v[164:165], v[164:165] op_sel_hi:[1,0,0]
	v_pk_fma_f32 v[182:183], v[182:183], v[164:165], v[164:165] op_sel_hi:[1,0,0]
	v_rcp_f32_e32 v176, v176
	v_rcp_f32_e32 v177, v177
	v_rcp_f32_e32 v178, v178
	v_rcp_f32_e32 v179, v179
	v_rcp_f32_e32 v180, v180
	v_rcp_f32_e32 v181, v181
	v_rcp_f32_e32 v182, v182
	v_rcp_f32_e32 v183, v183
	v_pk_mul_f32 v[20:21], v[20:21], v[28:29]
	v_pk_mul_f32 v[22:23], v[22:23], v[30:31]
	v_pk_mul_f32 v[16:17], v[16:17], v[24:25]
	v_pk_mul_f32 v[18:19], v[18:19], v[26:27]
	v_pk_mul_f32 v[176:177], v[20:21], v[176:177]
	v_pk_mul_f32 v[178:179], v[22:23], v[178:179]
	v_pk_mul_f32 v[180:181], v[16:17], v[180:181]
	v_pk_mul_f32 v[182:183], v[18:19], v[182:183]
	v_cvt_pk_bf16_f32 v192, v176, v177
	v_cvt_pk_bf16_f32 v193, v178, v179
	v_cvt_pk_bf16_f32 v194, v180, v181
	v_cvt_pk_bf16_f32 v195, v182, v183
	v_add_u32_e32 v200, 0xdc000, v248
	global_store_dwordx4 v200, v[192:195], s[48:49] sc0 sc1
	v_pk_mul_f32 v[184:185], v[4:5], v[166:167] op_sel_hi:[1,0]
	v_pk_mul_f32 v[186:187], v[6:7], v[166:167] op_sel_hi:[1,0]
	v_pk_mul_f32 v[188:189], v[0:1], v[166:167] op_sel_hi:[1,0]
	v_pk_mul_f32 v[190:191], v[2:3], v[166:167] op_sel_hi:[1,0]
	v_exp_f32_e32 v184, v184
	v_exp_f32_e32 v185, v185
	v_exp_f32_e32 v186, v186
	v_exp_f32_e32 v187, v187
	v_exp_f32_e32 v188, v188
	v_exp_f32_e32 v189, v189
	v_exp_f32_e32 v190, v190
	v_exp_f32_e32 v191, v191
	v_pk_fma_f32 v[184:185], v[184:185], v[168:169], v[168:169] op_sel_hi:[1,0,0]
	v_pk_fma_f32 v[186:187], v[186:187], v[168:169], v[168:169] op_sel_hi:[1,0,0]
	v_pk_fma_f32 v[188:189], v[188:189], v[168:169], v[168:169] op_sel_hi:[1,0,0]
	v_pk_fma_f32 v[190:191], v[190:191], v[168:169], v[168:169] op_sel_hi:[1,0,0]
	v_rcp_f32_e32 v184, v184
	v_rcp_f32_e32 v185, v185
	v_rcp_f32_e32 v186, v186
	v_rcp_f32_e32 v187, v187
	v_rcp_f32_e32 v188, v188
	v_rcp_f32_e32 v189, v189
	v_rcp_f32_e32 v190, v190
	v_rcp_f32_e32 v191, v191
	v_pk_mul_f32 v[4:5], v[4:5], v[12:13]
	v_pk_mul_f32 v[6:7], v[6:7], v[14:15]
	v_pk_mul_f32 v[0:1], v[0:1], v[8:9]
	v_pk_mul_f32 v[2:3], v[2:3], v[10:11]
	v_pk_mul_f32 v[184:185], v[4:5], v[184:185]
	v_pk_mul_f32 v[186:187], v[6:7], v[186:187]
	v_pk_mul_f32 v[188:189], v[0:1], v[188:189]
	v_pk_mul_f32 v[190:191], v[2:3], v[190:191]
	v_cvt_pk_bf16_f32 v196, v184, v185
	v_cvt_pk_bf16_f32 v197, v186, v187
	v_cvt_pk_bf16_f32 v198, v188, v189
	v_cvt_pk_bf16_f32 v199, v190, v191
	v_add_u32_e32 v201, 0xf2000, v248
	global_store_dwordx4 v201, v[196:199], s[48:49] sc0 sc1
